# v45 plus between-tile trims: scalar has-next test, simplified tile-order arithmetic, gelu-silu denominator as one fma, entry nop removed
# speedup vs baseline: 1.0035x; 1.0035x over previous
;     __device__ bool next(int i, Unit& u) const {
;         int t = i, b = 0; if (nb == 3) { t = i / 3; b = i - 3 * t; }
;         const long L = (long)t * G + c; if (L >= nwg) return false;
;         int wgid = (int)L; { const int q = nwg / NXCD, r = nwg % NXCD, xcd = wgid % NXCD, off = wgid / NXCD; wgid = (xcd < r ? xcd * (q + 1) : r * (q + 1) + (xcd - r) * q) + off; }
;         const int nig = WGM * nN, gid = wgid / nig, fm = gid * WGM, gsz = (nM - fm) < WGM ? (nM - fm) : WGM;
;         u.pm = fm + ((wgid % nig) % gsz); u.pn = (wgid % nig) / gsz; u.b = b; return true;
;     }
.LBB0_277:
	s_add_i32 s58, s58, 1
	v_readlane_b32 s6, v253, 5
	s_mul_i32 s6, s58, s6
	s_mul_hi_u32 s14, s58, s96
	s_add_i32 s6, s14, s6
	s_mul_i32 s14, s58, s96
	s_add_u32 s14, s14, s29
	v_readlane_b32 s15, v253, 4
	s_addc_u32 s15, s6, s15
	s_cmp_lt_u32 s14, 0x1800
	s_cselect_b64 s[40:41], -1, 0
	s_cbranch_scc0 .LBB0_279
	s_lshr_b32 s15, s14, 3
	s_and_b32 s6, s14, 7
	s_mulk_i32 s6, 0x300
	s_add_i32 s6, s6, s15
	s_mul_hi_u32 s14, s6, 0x2aaaaaab
	s_lshr_b32 s14, s14, 5
	s_lshl_b32 s15, s14, 2
	s_mulk_i32 s14, 0xc0
	s_sub_i32 s6, s6, s14
	s_lshr_b32 s16, s6, 2
	s_and_b32 s6, s6, 3
	s_add_i32 s18, s15, s6

;     __device__ __forceinline__ void operator()(f32x4 (&acc)[2][2][4][2], const Unit& u, int wr, int wc, int fr, int fq) const {
;         const int pn = u.pn;
;         int mode; size_t ocol;
;         if (pn < 8)       { mode = 4; ocol = S_YA + pn * 128; }
;         else if (pn < 12) { mode = 1; ocol = S_GV + (pn - 8) * 256; }
;         else if (pn < 16) { mode = 0; ocol = S_BP + (pn - 12) * 256; }
;         else if (pn < 24) { mode = 5; ocol = S_Q + (pn - 16) * 128; }
;         else if (pn < 32) { mode = 6; ocol = S_CBZ + (pn - 24) * 128; }
;         else              { mode = 7; ocol = 0; }
;         if (mode == 7) {
;             const int row0q = u.pm * BM + wr * 64 + fr; const int ch = 64 * (pn - 32) + 16 * wc + 4 * fq;
.LBB0_283:
	v_lshl_add_u32 v148, s60, 8, v164
	v_ashrrev_i32_e32 v149, 31, v148
	s_cmp_gt_u32 s59, 31
	s_cbranch_scc1 .LBB0_424
	v_lshlrev_b32_e32 v150, 11, v164
	v_lshl_add_u32 v150, v136, 1, v150
	s_lshl_b32 s14, s60, 19
	s_add_u32 s24, s70, s14
	s_addc_u32 s25, s71, 0
	s_cmp_lt_u32 s59, 8
	s_cbranch_scc1 .Lp1_epi_m4
	s_cmp_lt_u32 s59, 12
	s_cbranch_scc1 .Lp1_epi_m1
	s_cmp_lt_u32 s59, 16
	s_cbranch_scc1 .Lp1_epi_m0
	s_cmp_lt_u32 s59, 24
	s_cbranch_scc1 .Lp1_epi_m5

; __device__ __forceinline__ unsigned cvt_pk_bf16(float lo, float hi) { unsigned r; asm volatile("v_cvt_pk_bf16_f32 %0, %1, %2" : "=v"(r) : "v"(lo), "v"(hi)); return r; }
; __device__ __forceinline__ float sigmoid_f(float x) { return __builtin_amdgcn_rcpf(1.0f + __builtin_amdgcn_exp2f(-1.4426950409f * x)); }
;     __device__ __forceinline__ void operator()(f32x4 (&acc)[2][2][4][2], const Unit& u, int wr, int wc, int fr, int fq) const {
;     ...
;         const int row0 = u.pm * BM + wr * 64 + fr; const size_t col0 = ocol + wc * 32 + 8 * fq;
;         if (mode >= 4) {
; #pragma unroll
;             for (int ai = 0; ai < 2; ++ai)
; #pragma unroll
;                 for (int m = 0; m < 4; ++m) { bf16_t* rowp = O + (size_t)(row0 + ai * HALF + m * 16) * LDP + col0;
;                     float v[8];
; #pragma unroll
;                     for (int j = 0; j < 8; ++j) {
;                         const float x0 = acc[ai][0][m][j >> 2][j & 3], x1 = acc[ai][1][m][j >> 2][j & 3];
;                         const float f0 = (mode == 4) ? x0 * sigmoid_f(1.5957691216f * (x0 + 0.044715f * x0 * x0 * x0)) : x0;
;                         const float f1 = (mode == 5) ? x1 : x1 * sigmoid_f(x1);
;                         v[j] = f0 * f1;
;                     }
;                     u32x4 w; w.x = cvt_pk_bf16(v[0], v[1]); w.y = cvt_pk_bf16(v[2], v[3]); w.z = cvt_pk_bf16(v[4], v[5]); w.w = cvt_pk_bf16(v[6], v[7]);
;                     *(u32x4*)rowp = w; }
.Lp1_epi_m4:
	s_lshl_b32 s14, s59, 8
	s_add_u32 s24, s24, s14
	s_addc_u32 s25, s25, 0
	v_mov_b32_e32 v151, 0xbdd2d3e8
	v_mul_f32_e32 v152, v124, v124
	v_mul_f32_e32 v153, v125, v125
	v_mul_f32_e32 v154, v126, v126
	v_mul_f32_e32 v155, v127, v127
	v_mul_f32_e32 v156, v120, v120
	v_mul_f32_e32 v157, v121, v121
	v_mul_f32_e32 v158, v122, v122
	v_mul_f32_e32 v159, v123, v123
	v_mul_f32_e32 v168, 0xbfb8aa3b, v116
	v_mul_f32_e32 v169, 0xbfb8aa3b, v117
	v_mul_f32_e32 v170, 0xbfb8aa3b, v118
	v_mul_f32_e32 v171, 0xbfb8aa3b, v119
	v_mul_f32_e32 v172, 0xbfb8aa3b, v112
	v_mul_f32_e32 v173, 0xbfb8aa3b, v113
	v_mul_f32_e32 v174, 0xbfb8aa3b, v114
	v_mul_f32_e32 v175, 0xbfb8aa3b, v115
	v_fmaak_f32 v152, v151, v152, 0xc0135761
	v_fmaak_f32 v153, v151, v153, 0xc0135761
	v_fmaak_f32 v154, v151, v154, 0xc0135761
	v_fmaak_f32 v155, v151, v155, 0xc0135761
	v_fmaak_f32 v156, v151, v156, 0xc0135761
	v_fmaak_f32 v157, v151, v157, 0xc0135761
	v_fmaak_f32 v158, v151, v158, 0xc0135761
	v_fmaak_f32 v159, v151, v159, 0xc0135761
	v_exp_f32_e32 v168, v168
	v_exp_f32_e32 v169, v169
	v_exp_f32_e32 v170, v170
	v_exp_f32_e32 v171, v171
	v_exp_f32_e32 v172, v172
	v_exp_f32_e32 v173, v173
	v_exp_f32_e32 v174, v174
	v_exp_f32_e32 v175, v175
	v_mul_f32_e32 v152, v124, v152
	v_mul_f32_e32 v153, v125, v153
	v_mul_f32_e32 v154, v126, v154
	v_mul_f32_e32 v155, v127, v155
	v_mul_f32_e32 v156, v120, v156
	v_mul_f32_e32 v157, v121, v157
	v_mul_f32_e32 v158, v122, v158
	v_mul_f32_e32 v159, v123, v159
	v_exp_f32_e32 v152, v152
	v_exp_f32_e32 v153, v153
	v_exp_f32_e32 v154, v154
	v_exp_f32_e32 v155, v155
	v_exp_f32_e32 v156, v156
	v_exp_f32_e32 v157, v157
	v_exp_f32_e32 v158, v158
	v_exp_f32_e32 v159, v159
	v_add_f32_e32 v168, 1.0, v168
	v_add_f32_e32 v169, 1.0, v169
	v_add_f32_e32 v170, 1.0, v170
	v_add_f32_e32 v171, 1.0, v171
	v_add_f32_e32 v172, 1.0, v172
	v_add_f32_e32 v173, 1.0, v173
	v_add_f32_e32 v174, 1.0, v174
	v_add_f32_e32 v175, 1.0, v175
	v_fma_f32 v152, v152, v168, v168
	v_fma_f32 v153, v153, v169, v169
	v_fma_f32 v154, v154, v170, v170
	v_fma_f32 v155, v155, v171, v171
	v_fma_f32 v156, v156, v172, v172
	v_fma_f32 v157, v157, v173, v173
	v_fma_f32 v158, v158, v174, v174
	v_fma_f32 v159, v159, v175, v175
	v_mul_f32_e32 v168, v124, v116
	v_mul_f32_e32 v169, v125, v117
	v_mul_f32_e32 v170, v126, v118
	v_mul_f32_e32 v171, v127, v119
	v_mul_f32_e32 v172, v120, v112
	v_mul_f32_e32 v173, v121, v113
	v_mul_f32_e32 v174, v122, v114
	v_mul_f32_e32 v175, v123, v115
	v_rcp_f32_e32 v152, v152
	v_rcp_f32_e32 v153, v153
	v_rcp_f32_e32 v154, v154
	v_rcp_f32_e32 v155, v155
	v_rcp_f32_e32 v156, v156
	v_rcp_f32_e32 v157, v157
	v_rcp_f32_e32 v158, v158
	v_rcp_f32_e32 v159, v159
	s_nop 0
	v_mul_f32_e32 v152, v168, v152
	v_mul_f32_e32 v153, v169, v153
	v_mul_f32_e32 v154, v170, v154
	v_mul_f32_e32 v155, v171, v155
	v_mul_f32_e32 v156, v172, v156
	v_mul_f32_e32 v157, v173, v157
	v_mul_f32_e32 v158, v174, v158
	v_mul_f32_e32 v159, v175, v159
	v_cvt_pk_bf16_f32 v176, v152, v153
	v_cvt_pk_bf16_f32 v177, v154, v155
	v_cvt_pk_bf16_f32 v178, v156, v157
	v_cvt_pk_bf16_f32 v179, v158, v159
	global_store_dwordx4 v150, v[176:179], s[24:25]
	s_add_u32 s24, s24, 0x8000
	s_addc_u32 s25, s25, 0
	v_mul_f32_e32 v152, v108, v108
	v_mul_f32_e32 v153, v109, v109
	v_mul_f32_e32 v154, v110, v110
	v_mul_f32_e32 v155, v111, v111
	v_mul_f32_e32 v156, v104, v104
	v_mul_f32_e32 v157, v105, v105
	v_mul_f32_e32 v158, v106, v106
	v_mul_f32_e32 v159, v107, v107
	v_mul_f32_e32 v168, 0xbfb8aa3b, v100
	v_mul_f32_e32 v169, 0xbfb8aa3b, v101
	v_mul_f32_e32 v170, 0xbfb8aa3b, v102
	v_mul_f32_e32 v171, 0xbfb8aa3b, v103
	v_mul_f32_e32 v172, 0xbfb8aa3b, v96
	v_mul_f32_e32 v173, 0xbfb8aa3b, v97
	v_mul_f32_e32 v174, 0xbfb8aa3b, v98
	v_mul_f32_e32 v175, 0xbfb8aa3b, v99
	v_fmaak_f32 v152, v151, v152, 0xc0135761
	v_fmaak_f32 v153, v151, v153, 0xc0135761
	v_fmaak_f32 v154, v151, v154, 0xc0135761
	v_fmaak_f32 v155, v151, v155, 0xc0135761
	v_fmaak_f32 v156, v151, v156, 0xc0135761
	v_fmaak_f32 v157, v151, v157, 0xc0135761
	v_fmaak_f32 v158, v151, v158, 0xc0135761
	v_fmaak_f32 v159, v151, v159, 0xc0135761
	v_exp_f32_e32 v168, v168
	v_exp_f32_e32 v169, v169
	v_exp_f32_e32 v170, v170
	v_exp_f32_e32 v171, v171
	v_exp_f32_e32 v172, v172
	v_exp_f32_e32 v173, v173
	v_exp_f32_e32 v174, v174
	v_exp_f32_e32 v175, v175
	v_mul_f32_e32 v152, v108, v152
	v_mul_f32_e32 v153, v109, v153
	v_mul_f32_e32 v154, v110, v154
	v_mul_f32_e32 v155, v111, v155
	v_mul_f32_e32 v156, v104, v156
	v_mul_f32_e32 v157, v105, v157
	v_mul_f32_e32 v158, v106, v158
	v_mul_f32_e32 v159, v107, v159
	v_exp_f32_e32 v152, v152
	v_exp_f32_e32 v153, v153
	v_exp_f32_e32 v154, v154
	v_exp_f32_e32 v155, v155
	v_exp_f32_e32 v156, v156
	v_exp_f32_e32 v157, v157
	v_exp_f32_e32 v158, v158
	v_exp_f32_e32 v159, v159
	v_add_f32_e32 v168, 1.0, v168
	v_add_f32_e32 v169, 1.0, v169
	v_add_f32_e32 v170, 1.0, v170
	v_add_f32_e32 v171, 1.0, v171
	v_add_f32_e32 v172, 1.0, v172
	v_add_f32_e32 v173, 1.0, v173
	v_add_f32_e32 v174, 1.0, v174
	v_add_f32_e32 v175, 1.0, v175
	v_fma_f32 v152, v152, v168, v168
	v_fma_f32 v153, v153, v169, v169
	v_fma_f32 v154, v154, v170, v170
	v_fma_f32 v155, v155, v171, v171
	v_fma_f32 v156, v156, v172, v172
	v_fma_f32 v157, v157, v173, v173
	v_fma_f32 v158, v158, v174, v174
	v_fma_f32 v159, v159, v175, v175
	v_mul_f32_e32 v168, v108, v100
	v_mul_f32_e32 v169, v109, v101
	v_mul_f32_e32 v170, v110, v102
	v_mul_f32_e32 v171, v111, v103
	v_mul_f32_e32 v172, v104, v96
	v_mul_f32_e32 v173, v105, v97
	v_mul_f32_e32 v174, v106, v98
	v_mul_f32_e32 v175, v107, v99
	v_rcp_f32_e32 v152, v152
	v_rcp_f32_e32 v153, v153
	v_rcp_f32_e32 v154, v154
	v_rcp_f32_e32 v155, v155
	v_rcp_f32_e32 v156, v156
; __device__ __forceinline__ unsigned cvt_pk_bf16(float lo, float hi) { unsigned r; asm volatile("v_cvt_pk_bf16_f32 %0, %1, %2" : "=v"(r) : "v"(lo), "v"(hi)); return r; }
; __device__ __forceinline__ float sigmoid_f(float x) { return __builtin_amdgcn_rcpf(1.0f + __builtin_amdgcn_exp2f(-1.4426950409f * x)); }
;     __device__ __forceinline__ void operator()(f32x4 (&acc)[2][2][4][2], const Unit& u, int wr, int wc, int fr, int fq) const {
;     ...
;         const int row0 = u.pm * BM + wr * 64 + fr; const size_t col0 = ocol + wc * 32 + 8 * fq;
;         if (mode >= 4) {
; #pragma unroll
;             for (int ai = 0; ai < 2; ++ai)
; #pragma unroll
;                 for (int m = 0; m < 4; ++m) { bf16_t* rowp = O + (size_t)(row0 + ai * HALF + m * 16) * LDP + col0;
;                     float v[8];
; #pragma unroll
;                     for (int j = 0; j < 8; ++j) {
;                         const float x0 = acc[ai][0][m][j >> 2][j & 3], x1 = acc[ai][1][m][j >> 2][j & 3];
;                         const float f0 = (mode == 4) ? x0 * sigmoid_f(1.5957691216f * (x0 + 0.044715f * x0 * x0 * x0)) : x0;
;                         const float f1 = (mode == 5) ? x1 : x1 * sigmoid_f(x1);
;                         v[j] = f0 * f1;
;                     }
;                     u32x4 w; w.x = cvt_pk_bf16(v[0], v[1]); w.y = cvt_pk_bf16(v[2], v[3]); w.z = cvt_pk_bf16(v[4], v[5]); w.w = cvt_pk_bf16(v[6], v[7]);
;                     *(u32x4*)rowp = w; }
	v_rcp_f32_e32 v157, v157
	v_rcp_f32_e32 v158, v158
	v_rcp_f32_e32 v159, v159
	s_nop 0
	v_mul_f32_e32 v152, v168, v152
	v_mul_f32_e32 v153, v169, v153
	v_mul_f32_e32 v154, v170, v154
	v_mul_f32_e32 v155, v171, v155
	v_mul_f32_e32 v156, v172, v156
	v_mul_f32_e32 v157, v173, v157
	v_mul_f32_e32 v158, v174, v158
	v_mul_f32_e32 v159, v175, v159
	v_cvt_pk_bf16_f32 v180, v152, v153
	v_cvt_pk_bf16_f32 v181, v154, v155
	v_cvt_pk_bf16_f32 v182, v156, v157
	v_cvt_pk_bf16_f32 v183, v158, v159
	global_store_dwordx4 v150, v[180:183], s[24:25]
	s_add_u32 s24, s24, 0x8000
	s_addc_u32 s25, s25, 0
	v_mul_f32_e32 v152, v92, v92
	v_mul_f32_e32 v153, v93, v93
	v_mul_f32_e32 v154, v94, v94
	v_mul_f32_e32 v155, v95, v95
	v_mul_f32_e32 v156, v88, v88
	v_mul_f32_e32 v157, v89, v89
	v_mul_f32_e32 v158, v90, v90
	v_mul_f32_e32 v159, v91, v91
	v_mul_f32_e32 v168, 0xbfb8aa3b, v84
	v_mul_f32_e32 v169, 0xbfb8aa3b, v85
	v_mul_f32_e32 v170, 0xbfb8aa3b, v86
	v_mul_f32_e32 v171, 0xbfb8aa3b, v87
	v_mul_f32_e32 v172, 0xbfb8aa3b, v80
	v_mul_f32_e32 v173, 0xbfb8aa3b, v81
	v_mul_f32_e32 v174, 0xbfb8aa3b, v82
	v_mul_f32_e32 v175, 0xbfb8aa3b, v83
	v_fmaak_f32 v152, v151, v152, 0xc0135761
	v_fmaak_f32 v153, v151, v153, 0xc0135761
	v_fmaak_f32 v154, v151, v154, 0xc0135761
	v_fmaak_f32 v155, v151, v155, 0xc0135761
	v_fmaak_f32 v156, v151, v156, 0xc0135761
	v_fmaak_f32 v157, v151, v157, 0xc0135761
	v_fmaak_f32 v158, v151, v158, 0xc0135761
	v_fmaak_f32 v159, v151, v159, 0xc0135761
	v_exp_f32_e32 v168, v168
	v_exp_f32_e32 v169, v169
	v_exp_f32_e32 v170, v170
	v_exp_f32_e32 v171, v171
	v_exp_f32_e32 v172, v172
	v_exp_f32_e32 v173, v173
	v_exp_f32_e32 v174, v174
	v_exp_f32_e32 v175, v175
	v_mul_f32_e32 v152, v92, v152
	v_mul_f32_e32 v153, v93, v153
	v_mul_f32_e32 v154, v94, v154
	v_mul_f32_e32 v155, v95, v155
	v_mul_f32_e32 v156, v88, v156
	v_mul_f32_e32 v157, v89, v157
	v_mul_f32_e32 v158, v90, v158
	v_mul_f32_e32 v159, v91, v159
	v_exp_f32_e32 v152, v152
	v_exp_f32_e32 v153, v153
	v_exp_f32_e32 v154, v154
	v_exp_f32_e32 v155, v155
	v_exp_f32_e32 v156, v156
	v_exp_f32_e32 v157, v157
	v_exp_f32_e32 v158, v158
	v_exp_f32_e32 v159, v159
	v_add_f32_e32 v168, 1.0, v168
	v_add_f32_e32 v169, 1.0, v169
	v_add_f32_e32 v170, 1.0, v170
	v_add_f32_e32 v171, 1.0, v171
	v_add_f32_e32 v172, 1.0, v172
	v_add_f32_e32 v173, 1.0, v173
	v_add_f32_e32 v174, 1.0, v174
	v_add_f32_e32 v175, 1.0, v175
	v_fma_f32 v152, v152, v168, v168
	v_fma_f32 v153, v153, v169, v169
	v_fma_f32 v154, v154, v170, v170
	v_fma_f32 v155, v155, v171, v171
	v_fma_f32 v156, v156, v172, v172
	v_fma_f32 v157, v157, v173, v173
	v_fma_f32 v158, v158, v174, v174
	v_fma_f32 v159, v159, v175, v175
	v_mul_f32_e32 v168, v92, v84
	v_mul_f32_e32 v169, v93, v85
	v_mul_f32_e32 v170, v94, v86
	v_mul_f32_e32 v171, v95, v87
	v_mul_f32_e32 v172, v88, v80
	v_mul_f32_e32 v173, v89, v81
	v_mul_f32_e32 v174, v90, v82
	v_mul_f32_e32 v175, v91, v83
	v_rcp_f32_e32 v152, v152
	v_rcp_f32_e32 v153, v153
	v_rcp_f32_e32 v154, v154
	v_rcp_f32_e32 v155, v155
	v_rcp_f32_e32 v156, v156
	v_rcp_f32_e32 v157, v157
	v_rcp_f32_e32 v158, v158
	v_rcp_f32_e32 v159, v159
	s_nop 0
	v_mul_f32_e32 v152, v168, v152
	v_mul_f32_e32 v153, v169, v153
	v_mul_f32_e32 v154, v170, v154
	v_mul_f32_e32 v155, v171, v155
	v_mul_f32_e32 v156, v172, v156
	v_mul_f32_e32 v157, v173, v157
	v_mul_f32_e32 v158, v174, v158
	v_mul_f32_e32 v159, v175, v159
	v_cvt_pk_bf16_f32 v176, v152, v153
	v_cvt_pk_bf16_f32 v177, v154, v155
	v_cvt_pk_bf16_f32 v178, v156, v157
	v_cvt_pk_bf16_f32 v179, v158, v159
	global_store_dwordx4 v150, v[176:179], s[24:25]
	s_add_u32 s24, s24, 0x8000
	s_addc_u32 s25, s25, 0
	v_mul_f32_e32 v152, v76, v76
	v_mul_f32_e32 v153, v77, v77
	v_mul_f32_e32 v154, v78, v78
	v_mul_f32_e32 v155, v79, v79
	v_mul_f32_e32 v156, v72, v72
	v_mul_f32_e32 v157, v73, v73
	v_mul_f32_e32 v158, v74, v74
	v_mul_f32_e32 v159, v75, v75
	v_mul_f32_e32 v168, 0xbfb8aa3b, v68
	v_mul_f32_e32 v169, 0xbfb8aa3b, v69
	v_mul_f32_e32 v170, 0xbfb8aa3b, v70
	v_mul_f32_e32 v171, 0xbfb8aa3b, v71
	v_mul_f32_e32 v172, 0xbfb8aa3b, v64
	v_mul_f32_e32 v173, 0xbfb8aa3b, v65
	v_mul_f32_e32 v174, 0xbfb8aa3b, v66
	v_mul_f32_e32 v175, 0xbfb8aa3b, v67
	v_fmaak_f32 v152, v151, v152, 0xc0135761
	v_fmaak_f32 v153, v151, v153, 0xc0135761
	v_fmaak_f32 v154, v151, v154, 0xc0135761
	v_fmaak_f32 v155, v151, v155, 0xc0135761
	v_fmaak_f32 v156, v151, v156, 0xc0135761
	v_fmaak_f32 v157, v151, v157, 0xc0135761
	v_fmaak_f32 v158, v151, v158, 0xc0135761
	v_fmaak_f32 v159, v151, v159, 0xc0135761
	v_exp_f32_e32 v168, v168
	v_exp_f32_e32 v169, v169
	v_exp_f32_e32 v170, v170
	v_exp_f32_e32 v171, v171
	v_exp_f32_e32 v172, v172
	v_exp_f32_e32 v173, v173
	v_exp_f32_e32 v174, v174
	v_exp_f32_e32 v175, v175
	v_mul_f32_e32 v152, v76, v152
	v_mul_f32_e32 v153, v77, v153
	v_mul_f32_e32 v154, v78, v154
	v_mul_f32_e32 v155, v79, v155
	v_mul_f32_e32 v156, v72, v156
	v_mul_f32_e32 v157, v73, v157
	v_mul_f32_e32 v158, v74, v158
	v_mul_f32_e32 v159, v75, v159
	v_exp_f32_e32 v152, v152
	v_exp_f32_e32 v153, v153
	v_exp_f32_e32 v154, v154
	v_exp_f32_e32 v155, v155
	v_exp_f32_e32 v156, v156
	v_exp_f32_e32 v157, v157
	v_exp_f32_e32 v158, v158
	v_exp_f32_e32 v159, v159
	v_add_f32_e32 v168, 1.0, v168
	v_add_f32_e32 v169, 1.0, v169
	v_add_f32_e32 v170, 1.0, v170
	v_add_f32_e32 v171, 1.0, v171
	v_add_f32_e32 v172, 1.0, v172
	v_add_f32_e32 v173, 1.0, v173
	v_add_f32_e32 v174, 1.0, v174
	v_add_f32_e32 v175, 1.0, v175
	v_fma_f32 v152, v152, v168, v168
	v_fma_f32 v153, v153, v169, v169
	v_fma_f32 v154, v154, v170, v170
	v_fma_f32 v155, v155, v171, v171
	v_fma_f32 v156, v156, v172, v172
	v_fma_f32 v157, v157, v173, v173
	v_fma_f32 v158, v158, v174, v174
; __device__ __forceinline__ unsigned cvt_pk_bf16(float lo, float hi) { unsigned r; asm volatile("v_cvt_pk_bf16_f32 %0, %1, %2" : "=v"(r) : "v"(lo), "v"(hi)); return r; }
; __device__ __forceinline__ float sigmoid_f(float x) { return __builtin_amdgcn_rcpf(1.0f + __builtin_amdgcn_exp2f(-1.4426950409f * x)); }
;     __device__ __forceinline__ void operator()(f32x4 (&acc)[2][2][4][2], const Unit& u, int wr, int wc, int fr, int fq) const {
;     ...
;         const int row0 = u.pm * BM + wr * 64 + fr; const size_t col0 = ocol + wc * 32 + 8 * fq;
;         if (mode >= 4) {
; #pragma unroll
;             for (int ai = 0; ai < 2; ++ai)
; #pragma unroll
;                 for (int m = 0; m < 4; ++m) { bf16_t* rowp = O + (size_t)(row0 + ai * HALF + m * 16) * LDP + col0;
;                     float v[8];
; #pragma unroll
;                     for (int j = 0; j < 8; ++j) {
;                         const float x0 = acc[ai][0][m][j >> 2][j & 3], x1 = acc[ai][1][m][j >> 2][j & 3];
;                         const float f0 = (mode == 4) ? x0 * sigmoid_f(1.5957691216f * (x0 + 0.044715f * x0 * x0 * x0)) : x0;
;                         const float f1 = (mode == 5) ? x1 : x1 * sigmoid_f(x1);
;                         v[j] = f0 * f1;
;                     }
;                     u32x4 w; w.x = cvt_pk_bf16(v[0], v[1]); w.y = cvt_pk_bf16(v[2], v[3]); w.z = cvt_pk_bf16(v[4], v[5]); w.w = cvt_pk_bf16(v[6], v[7]);
;                     *(u32x4*)rowp = w; }
	v_fma_f32 v159, v159, v175, v175
	v_mul_f32_e32 v168, v76, v68
	v_mul_f32_e32 v169, v77, v69
	v_mul_f32_e32 v170, v78, v70
	v_mul_f32_e32 v171, v79, v71
	v_mul_f32_e32 v172, v72, v64
	v_mul_f32_e32 v173, v73, v65
	v_mul_f32_e32 v174, v74, v66
	v_mul_f32_e32 v175, v75, v67
	v_rcp_f32_e32 v152, v152
	v_rcp_f32_e32 v153, v153
	v_rcp_f32_e32 v154, v154
	v_rcp_f32_e32 v155, v155
	v_rcp_f32_e32 v156, v156
	v_rcp_f32_e32 v157, v157
	v_rcp_f32_e32 v158, v158
	v_rcp_f32_e32 v159, v159
	s_nop 0
	v_mul_f32_e32 v152, v168, v152
	v_mul_f32_e32 v153, v169, v153
	v_mul_f32_e32 v154, v170, v154
	v_mul_f32_e32 v155, v171, v155
	v_mul_f32_e32 v156, v172, v156
	v_mul_f32_e32 v157, v173, v157
	v_mul_f32_e32 v158, v174, v158
	v_mul_f32_e32 v159, v175, v159
	v_cvt_pk_bf16_f32 v180, v152, v153
	v_cvt_pk_bf16_f32 v181, v154, v155
	v_cvt_pk_bf16_f32 v182, v156, v157
	v_cvt_pk_bf16_f32 v183, v158, v159
	global_store_dwordx4 v150, v[180:183], s[24:25]
	s_add_u32 s24, s24, 0x28000
	s_addc_u32 s25, s25, 0
	v_mul_f32_e32 v152, v60, v60
	v_mul_f32_e32 v153, v61, v61
	v_mul_f32_e32 v154, v62, v62
	v_mul_f32_e32 v155, v63, v63
	v_mul_f32_e32 v156, v56, v56
	v_mul_f32_e32 v157, v57, v57
	v_mul_f32_e32 v158, v58, v58
	v_mul_f32_e32 v159, v59, v59
	v_mul_f32_e32 v168, 0xbfb8aa3b, v52
	v_mul_f32_e32 v169, 0xbfb8aa3b, v53
	v_mul_f32_e32 v170, 0xbfb8aa3b, v54
	v_mul_f32_e32 v171, 0xbfb8aa3b, v55
	v_mul_f32_e32 v172, 0xbfb8aa3b, v48
	v_mul_f32_e32 v173, 0xbfb8aa3b, v49
	v_mul_f32_e32 v174, 0xbfb8aa3b, v50
	v_mul_f32_e32 v175, 0xbfb8aa3b, v51
	v_fmaak_f32 v152, v151, v152, 0xc0135761
	v_fmaak_f32 v153, v151, v153, 0xc0135761
	v_fmaak_f32 v154, v151, v154, 0xc0135761
	v_fmaak_f32 v155, v151, v155, 0xc0135761
	v_fmaak_f32 v156, v151, v156, 0xc0135761
	v_fmaak_f32 v157, v151, v157, 0xc0135761
	v_fmaak_f32 v158, v151, v158, 0xc0135761
	v_fmaak_f32 v159, v151, v159, 0xc0135761
	v_exp_f32_e32 v168, v168
	v_exp_f32_e32 v169, v169
	v_exp_f32_e32 v170, v170
	v_exp_f32_e32 v171, v171
	v_exp_f32_e32 v172, v172
	v_exp_f32_e32 v173, v173
	v_exp_f32_e32 v174, v174
	v_exp_f32_e32 v175, v175
	v_mul_f32_e32 v152, v60, v152
	v_mul_f32_e32 v153, v61, v153
	v_mul_f32_e32 v154, v62, v154
	v_mul_f32_e32 v155, v63, v155
	v_mul_f32_e32 v156, v56, v156
	v_mul_f32_e32 v157, v57, v157
	v_mul_f32_e32 v158, v58, v158
	v_mul_f32_e32 v159, v59, v159
	v_exp_f32_e32 v152, v152
	v_exp_f32_e32 v153, v153
	v_exp_f32_e32 v154, v154
	v_exp_f32_e32 v155, v155
	v_exp_f32_e32 v156, v156
	v_exp_f32_e32 v157, v157
	v_exp_f32_e32 v158, v158
	v_exp_f32_e32 v159, v159
	v_add_f32_e32 v168, 1.0, v168
	v_add_f32_e32 v169, 1.0, v169
	v_add_f32_e32 v170, 1.0, v170
	v_add_f32_e32 v171, 1.0, v171
	v_add_f32_e32 v172, 1.0, v172
	v_add_f32_e32 v173, 1.0, v173
	v_add_f32_e32 v174, 1.0, v174
	v_add_f32_e32 v175, 1.0, v175
	v_fma_f32 v152, v152, v168, v168
	v_fma_f32 v153, v153, v169, v169
	v_fma_f32 v154, v154, v170, v170
	v_fma_f32 v155, v155, v171, v171
	v_fma_f32 v156, v156, v172, v172
	v_fma_f32 v157, v157, v173, v173
	v_fma_f32 v158, v158, v174, v174
	v_fma_f32 v159, v159, v175, v175
	v_mul_f32_e32 v168, v60, v52
	v_mul_f32_e32 v169, v61, v53
	v_mul_f32_e32 v170, v62, v54
	v_mul_f32_e32 v171, v63, v55
	v_mul_f32_e32 v172, v56, v48
	v_mul_f32_e32 v173, v57, v49
	v_mul_f32_e32 v174, v58, v50
	v_mul_f32_e32 v175, v59, v51
	v_rcp_f32_e32 v152, v152
	v_rcp_f32_e32 v153, v153
	v_rcp_f32_e32 v154, v154
	v_rcp_f32_e32 v155, v155
	v_rcp_f32_e32 v156, v156
	v_rcp_f32_e32 v157, v157
	v_rcp_f32_e32 v158, v158
	v_rcp_f32_e32 v159, v159
	s_nop 0
	v_mul_f32_e32 v152, v168, v152
	v_mul_f32_e32 v153, v169, v153
	v_mul_f32_e32 v154, v170, v154
	v_mul_f32_e32 v155, v171, v155
	v_mul_f32_e32 v156, v172, v156
	v_mul_f32_e32 v157, v173, v157
	v_mul_f32_e32 v158, v174, v158
	v_mul_f32_e32 v159, v175, v159
	v_cvt_pk_bf16_f32 v176, v152, v153
	v_cvt_pk_bf16_f32 v177, v154, v155
	v_cvt_pk_bf16_f32 v178, v156, v157
	v_cvt_pk_bf16_f32 v179, v158, v159
	global_store_dwordx4 v150, v[176:179], s[24:25]
	s_add_u32 s24, s24, 0x8000
	s_addc_u32 s25, s25, 0
	v_mul_f32_e32 v152, v44, v44
	v_mul_f32_e32 v153, v45, v45
	v_mul_f32_e32 v154, v46, v46
	v_mul_f32_e32 v155, v47, v47
	v_mul_f32_e32 v156, v40, v40
	v_mul_f32_e32 v157, v41, v41
	v_mul_f32_e32 v158, v42, v42
	v_mul_f32_e32 v159, v43, v43
	v_mul_f32_e32 v168, 0xbfb8aa3b, v36
	v_mul_f32_e32 v169, 0xbfb8aa3b, v37
	v_mul_f32_e32 v170, 0xbfb8aa3b, v38
	v_mul_f32_e32 v171, 0xbfb8aa3b, v39
	v_mul_f32_e32 v172, 0xbfb8aa3b, v32
	v_mul_f32_e32 v173, 0xbfb8aa3b, v33
	v_mul_f32_e32 v174, 0xbfb8aa3b, v34
	v_mul_f32_e32 v175, 0xbfb8aa3b, v35
	v_fmaak_f32 v152, v151, v152, 0xc0135761
	v_fmaak_f32 v153, v151, v153, 0xc0135761
	v_fmaak_f32 v154, v151, v154, 0xc0135761
	v_fmaak_f32 v155, v151, v155, 0xc0135761
	v_fmaak_f32 v156, v151, v156, 0xc0135761
	v_fmaak_f32 v157, v151, v157, 0xc0135761
	v_fmaak_f32 v158, v151, v158, 0xc0135761
	v_fmaak_f32 v159, v151, v159, 0xc0135761
	v_exp_f32_e32 v168, v168
	v_exp_f32_e32 v169, v169
	v_exp_f32_e32 v170, v170
	v_exp_f32_e32 v171, v171
	v_exp_f32_e32 v172, v172
	v_exp_f32_e32 v173, v173
	v_exp_f32_e32 v174, v174
	v_exp_f32_e32 v175, v175
	v_mul_f32_e32 v152, v44, v152
	v_mul_f32_e32 v153, v45, v153
	v_mul_f32_e32 v154, v46, v154
	v_mul_f32_e32 v155, v47, v155
	v_mul_f32_e32 v156, v40, v156
	v_mul_f32_e32 v157, v41, v157
	v_mul_f32_e32 v158, v42, v158
	v_mul_f32_e32 v159, v43, v159
	v_exp_f32_e32 v152, v152
	v_exp_f32_e32 v153, v153
	v_exp_f32_e32 v154, v154
	v_exp_f32_e32 v155, v155
	v_exp_f32_e32 v156, v156
	v_exp_f32_e32 v157, v157
	v_exp_f32_e32 v158, v158
	v_exp_f32_e32 v159, v159
	v_add_f32_e32 v168, 1.0, v168
	v_add_f32_e32 v169, 1.0, v169
	v_add_f32_e32 v170, 1.0, v170
; __device__ __forceinline__ unsigned cvt_pk_bf16(float lo, float hi) { unsigned r; asm volatile("v_cvt_pk_bf16_f32 %0, %1, %2" : "=v"(r) : "v"(lo), "v"(hi)); return r; }
; __device__ __forceinline__ float sigmoid_f(float x) { return __builtin_amdgcn_rcpf(1.0f + __builtin_amdgcn_exp2f(-1.4426950409f * x)); }
;     __device__ __forceinline__ void operator()(f32x4 (&acc)[2][2][4][2], const Unit& u, int wr, int wc, int fr, int fq) const {
;     ...
;         const int row0 = u.pm * BM + wr * 64 + fr; const size_t col0 = ocol + wc * 32 + 8 * fq;
;         if (mode >= 4) {
; #pragma unroll
;             for (int ai = 0; ai < 2; ++ai)
; #pragma unroll
;                 for (int m = 0; m < 4; ++m) { bf16_t* rowp = O + (size_t)(row0 + ai * HALF + m * 16) * LDP + col0;
;                     float v[8];
; #pragma unroll
;                     for (int j = 0; j < 8; ++j) {
;                         const float x0 = acc[ai][0][m][j >> 2][j & 3], x1 = acc[ai][1][m][j >> 2][j & 3];
;                         const float f0 = (mode == 4) ? x0 * sigmoid_f(1.5957691216f * (x0 + 0.044715f * x0 * x0 * x0)) : x0;
;                         const float f1 = (mode == 5) ? x1 : x1 * sigmoid_f(x1);
;                         v[j] = f0 * f1;
;                     }
;                     u32x4 w; w.x = cvt_pk_bf16(v[0], v[1]); w.y = cvt_pk_bf16(v[2], v[3]); w.z = cvt_pk_bf16(v[4], v[5]); w.w = cvt_pk_bf16(v[6], v[7]);
;                     *(u32x4*)rowp = w; }
	v_add_f32_e32 v171, 1.0, v171
	v_add_f32_e32 v172, 1.0, v172
	v_add_f32_e32 v173, 1.0, v173
	v_add_f32_e32 v174, 1.0, v174
	v_add_f32_e32 v175, 1.0, v175
	v_fma_f32 v152, v152, v168, v168
	v_fma_f32 v153, v153, v169, v169
	v_fma_f32 v154, v154, v170, v170
	v_fma_f32 v155, v155, v171, v171
	v_fma_f32 v156, v156, v172, v172
	v_fma_f32 v157, v157, v173, v173
	v_fma_f32 v158, v158, v174, v174
	v_fma_f32 v159, v159, v175, v175
	v_mul_f32_e32 v168, v44, v36
	v_mul_f32_e32 v169, v45, v37
	v_mul_f32_e32 v170, v46, v38
	v_mul_f32_e32 v171, v47, v39
	v_mul_f32_e32 v172, v40, v32
	v_mul_f32_e32 v173, v41, v33
	v_mul_f32_e32 v174, v42, v34
	v_mul_f32_e32 v175, v43, v35
	v_rcp_f32_e32 v152, v152
	v_rcp_f32_e32 v153, v153
	v_rcp_f32_e32 v154, v154
	v_rcp_f32_e32 v155, v155
	v_rcp_f32_e32 v156, v156
	v_rcp_f32_e32 v157, v157
	v_rcp_f32_e32 v158, v158
	v_rcp_f32_e32 v159, v159
	s_nop 0
	v_mul_f32_e32 v152, v168, v152
	v_mul_f32_e32 v153, v169, v153
	v_mul_f32_e32 v154, v170, v154
	v_mul_f32_e32 v155, v171, v155
	v_mul_f32_e32 v156, v172, v156
	v_mul_f32_e32 v157, v173, v157
	v_mul_f32_e32 v158, v174, v158
	v_mul_f32_e32 v159, v175, v159
	v_cvt_pk_bf16_f32 v180, v152, v153
	v_cvt_pk_bf16_f32 v181, v154, v155
	v_cvt_pk_bf16_f32 v182, v156, v157
	v_cvt_pk_bf16_f32 v183, v158, v159
	global_store_dwordx4 v150, v[180:183], s[24:25]
	s_add_u32 s24, s24, 0x8000
	s_addc_u32 s25, s25, 0
	v_mul_f32_e32 v152, v28, v28
	v_mul_f32_e32 v153, v29, v29
	v_mul_f32_e32 v154, v30, v30
	v_mul_f32_e32 v155, v31, v31
	v_mul_f32_e32 v156, v24, v24
	v_mul_f32_e32 v157, v25, v25
	v_mul_f32_e32 v158, v26, v26
	v_mul_f32_e32 v159, v27, v27
	v_mul_f32_e32 v168, 0xbfb8aa3b, v20
	v_mul_f32_e32 v169, 0xbfb8aa3b, v21
	v_mul_f32_e32 v170, 0xbfb8aa3b, v22
	v_mul_f32_e32 v171, 0xbfb8aa3b, v23
	v_mul_f32_e32 v172, 0xbfb8aa3b, v16
	v_mul_f32_e32 v173, 0xbfb8aa3b, v17
	v_mul_f32_e32 v174, 0xbfb8aa3b, v18
	v_mul_f32_e32 v175, 0xbfb8aa3b, v19
	v_fmaak_f32 v152, v151, v152, 0xc0135761
	v_fmaak_f32 v153, v151, v153, 0xc0135761
	v_fmaak_f32 v154, v151, v154, 0xc0135761
	v_fmaak_f32 v155, v151, v155, 0xc0135761
	v_fmaak_f32 v156, v151, v156, 0xc0135761
	v_fmaak_f32 v157, v151, v157, 0xc0135761
	v_fmaak_f32 v158, v151, v158, 0xc0135761
	v_fmaak_f32 v159, v151, v159, 0xc0135761
	v_exp_f32_e32 v168, v168
	v_exp_f32_e32 v169, v169
	v_exp_f32_e32 v170, v170
	v_exp_f32_e32 v171, v171
	v_exp_f32_e32 v172, v172
	v_exp_f32_e32 v173, v173
	v_exp_f32_e32 v174, v174
	v_exp_f32_e32 v175, v175
	v_mul_f32_e32 v152, v28, v152
	v_mul_f32_e32 v153, v29, v153
	v_mul_f32_e32 v154, v30, v154
	v_mul_f32_e32 v155, v31, v155
	v_mul_f32_e32 v156, v24, v156
	v_mul_f32_e32 v157, v25, v157
	v_mul_f32_e32 v158, v26, v158
	v_mul_f32_e32 v159, v27, v159
	v_exp_f32_e32 v152, v152
	v_exp_f32_e32 v153, v153
	v_exp_f32_e32 v154, v154
	v_exp_f32_e32 v155, v155
	v_exp_f32_e32 v156, v156
	v_exp_f32_e32 v157, v157
	v_exp_f32_e32 v158, v158
	v_exp_f32_e32 v159, v159
	v_add_f32_e32 v168, 1.0, v168
	v_add_f32_e32 v169, 1.0, v169
	v_add_f32_e32 v170, 1.0, v170
	v_add_f32_e32 v171, 1.0, v171
	v_add_f32_e32 v172, 1.0, v172
	v_add_f32_e32 v173, 1.0, v173
	v_add_f32_e32 v174, 1.0, v174
	v_add_f32_e32 v175, 1.0, v175
	v_fma_f32 v152, v152, v168, v168
	v_fma_f32 v153, v153, v169, v169
	v_fma_f32 v154, v154, v170, v170
	v_fma_f32 v155, v155, v171, v171
	v_fma_f32 v156, v156, v172, v172
	v_fma_f32 v157, v157, v173, v173
	v_fma_f32 v158, v158, v174, v174
	v_fma_f32 v159, v159, v175, v175
	v_mul_f32_e32 v168, v28, v20
	v_mul_f32_e32 v169, v29, v21
	v_mul_f32_e32 v170, v30, v22
	v_mul_f32_e32 v171, v31, v23
	v_mul_f32_e32 v172, v24, v16
	v_mul_f32_e32 v173, v25, v17
	v_mul_f32_e32 v174, v26, v18
	v_mul_f32_e32 v175, v27, v19
; __device__ __forceinline__ unsigned cvt_pk_bf16(float lo, float hi) { unsigned r; asm volatile("v_cvt_pk_bf16_f32 %0, %1, %2" : "=v"(r) : "v"(lo), "v"(hi)); return r; }
; __device__ __forceinline__ float sigmoid_f(float x) { return __builtin_amdgcn_rcpf(1.0f + __builtin_amdgcn_exp2f(-1.4426950409f * x)); }
;     __device__ __forceinline__ void operator()(f32x4 (&acc)[2][2][4][2], const Unit& u, int wr, int wc, int fr, int fq) const {
;     ...
;         const int row0 = u.pm * BM + wr * 64 + fr; const size_t col0 = ocol + wc * 32 + 8 * fq;
;         if (mode >= 4) {
; #pragma unroll
;             for (int ai = 0; ai < 2; ++ai)
; #pragma unroll
;                 for (int m = 0; m < 4; ++m) { bf16_t* rowp = O + (size_t)(row0 + ai * HALF + m * 16) * LDP + col0;
;                     float v[8];
; #pragma unroll
;                     for (int j = 0; j < 8; ++j) {
;                         const float x0 = acc[ai][0][m][j >> 2][j & 3], x1 = acc[ai][1][m][j >> 2][j & 3];
;                         const float f0 = (mode == 4) ? x0 * sigmoid_f(1.5957691216f * (x0 + 0.044715f * x0 * x0 * x0)) : x0;
;                         const float f1 = (mode == 5) ? x1 : x1 * sigmoid_f(x1);
;                         v[j] = f0 * f1;
;                     }
;                     u32x4 w; w.x = cvt_pk_bf16(v[0], v[1]); w.y = cvt_pk_bf16(v[2], v[3]); w.z = cvt_pk_bf16(v[4], v[5]); w.w = cvt_pk_bf16(v[6], v[7]);
;                     *(u32x4*)rowp = w; }
	v_rcp_f32_e32 v152, v152
	v_rcp_f32_e32 v153, v153
	v_rcp_f32_e32 v154, v154
	v_rcp_f32_e32 v155, v155
	v_rcp_f32_e32 v156, v156
	v_rcp_f32_e32 v157, v157
	v_rcp_f32_e32 v158, v158
	v_rcp_f32_e32 v159, v159
	s_nop 0
	v_mul_f32_e32 v152, v168, v152
	v_mul_f32_e32 v153, v169, v153
	v_mul_f32_e32 v154, v170, v154
	v_mul_f32_e32 v155, v171, v155
	v_mul_f32_e32 v156, v172, v156
	v_mul_f32_e32 v157, v173, v157
	v_mul_f32_e32 v158, v174, v158
	v_mul_f32_e32 v159, v175, v159
	v_cvt_pk_bf16_f32 v176, v152, v153
	v_cvt_pk_bf16_f32 v177, v154, v155
	v_cvt_pk_bf16_f32 v178, v156, v157
	v_cvt_pk_bf16_f32 v179, v158, v159
	global_store_dwordx4 v150, v[176:179], s[24:25]
	s_add_u32 s24, s24, 0x8000
	s_addc_u32 s25, s25, 0
	v_mul_f32_e32 v152, v12, v12
	v_mul_f32_e32 v153, v13, v13
	v_mul_f32_e32 v154, v14, v14
	v_mul_f32_e32 v155, v15, v15
	v_mul_f32_e32 v156, v8, v8
	v_mul_f32_e32 v157, v9, v9
	v_mul_f32_e32 v158, v10, v10
	v_mul_f32_e32 v159, v11, v11
	v_mul_f32_e32 v168, 0xbfb8aa3b, v4
	v_mul_f32_e32 v169, 0xbfb8aa3b, v5
	v_mul_f32_e32 v170, 0xbfb8aa3b, v6
	v_mul_f32_e32 v171, 0xbfb8aa3b, v7
	v_mul_f32_e32 v172, 0xbfb8aa3b, v0
	v_mul_f32_e32 v173, 0xbfb8aa3b, v1
	v_mul_f32_e32 v174, 0xbfb8aa3b, v2
	v_mul_f32_e32 v175, 0xbfb8aa3b, v3
	v_fmaak_f32 v152, v151, v152, 0xc0135761
	v_fmaak_f32 v153, v151, v153, 0xc0135761
	v_fmaak_f32 v154, v151, v154, 0xc0135761
	v_fmaak_f32 v155, v151, v155, 0xc0135761
	v_fmaak_f32 v156, v151, v156, 0xc0135761
	v_fmaak_f32 v157, v151, v157, 0xc0135761
	v_fmaak_f32 v158, v151, v158, 0xc0135761
	v_fmaak_f32 v159, v151, v159, 0xc0135761
	v_exp_f32_e32 v168, v168
	v_exp_f32_e32 v169, v169
	v_exp_f32_e32 v170, v170
	v_exp_f32_e32 v171, v171
	v_exp_f32_e32 v172, v172
	v_exp_f32_e32 v173, v173
	v_exp_f32_e32 v174, v174
	v_exp_f32_e32 v175, v175
	v_mul_f32_e32 v152, v12, v152
	v_mul_f32_e32 v153, v13, v153
	v_mul_f32_e32 v154, v14, v154
	v_mul_f32_e32 v155, v15, v155
	v_mul_f32_e32 v156, v8, v156
	v_mul_f32_e32 v157, v9, v157
	v_mul_f32_e32 v158, v10, v158
	v_mul_f32_e32 v159, v11, v159
	v_exp_f32_e32 v152, v152
	v_exp_f32_e32 v153, v153
	v_exp_f32_e32 v154, v154
	v_exp_f32_e32 v155, v155
	v_exp_f32_e32 v156, v156
	v_exp_f32_e32 v157, v157
	v_exp_f32_e32 v158, v158
	v_exp_f32_e32 v159, v159
	v_add_f32_e32 v168, 1.0, v168
	v_add_f32_e32 v169, 1.0, v169
	v_add_f32_e32 v170, 1.0, v170
	v_add_f32_e32 v171, 1.0, v171
	v_add_f32_e32 v172, 1.0, v172
	v_add_f32_e32 v173, 1.0, v173
	v_add_f32_e32 v174, 1.0, v174
	v_add_f32_e32 v175, 1.0, v175
	v_fma_f32 v152, v152, v168, v168
	v_fma_f32 v153, v153, v169, v169
	v_fma_f32 v154, v154, v170, v170
	v_fma_f32 v155, v155, v171, v171
	v_fma_f32 v156, v156, v172, v172
	v_fma_f32 v157, v157, v173, v173
	v_fma_f32 v158, v158, v174, v174
	v_fma_f32 v159, v159, v175, v175
	v_mul_f32_e32 v168, v12, v4
	v_mul_f32_e32 v169, v13, v5
	v_mul_f32_e32 v170, v14, v6
	v_mul_f32_e32 v171, v15, v7
	v_mul_f32_e32 v172, v8, v0
	v_mul_f32_e32 v173, v9, v1
	v_mul_f32_e32 v174, v10, v2
	v_mul_f32_e32 v175, v11, v3
	v_rcp_f32_e32 v152, v152
	v_rcp_f32_e32 v153, v153
	v_rcp_f32_e32 v154, v154
	v_rcp_f32_e32 v155, v155
	v_rcp_f32_e32 v156, v156
	v_rcp_f32_e32 v157, v157
	v_rcp_f32_e32 v158, v158
	v_rcp_f32_e32 v159, v159
	s_nop 0
	v_mul_f32_e32 v152, v168, v152
	v_mul_f32_e32 v153, v169, v153
	v_mul_f32_e32 v154, v170, v154
	v_mul_f32_e32 v155, v171, v155
	v_mul_f32_e32 v156, v172, v156
	v_mul_f32_e32 v157, v173, v157
	v_mul_f32_e32 v158, v174, v158
	v_mul_f32_e32 v159, v175, v159
	v_cvt_pk_bf16_f32 v180, v152, v153
	v_cvt_pk_bf16_f32 v181, v154, v155
	v_cvt_pk_bf16_f32 v182, v156, v157
	v_cvt_pk_bf16_f32 v183, v158, v159
	global_store_dwordx4 v150, v[180:183], s[24:25]
	s_branch .LBB0_298
